# attention loops: V-tile row interleave before the LDS store done with 2 v_perm_b32 per dword pair instead of 4 and/shift/or ops
# speedup vs baseline: 1.0091x; 1.0035x over previous
; template <int DQ, int TYPE>
; __device__ __forceinline__ void attn_item(PP p, int layer, int b, int h, int qt, char* lds, const int tid_, unsigned* next_ctr, volatile XLAS unsigned* slot) {
;     ...
;     f32x16 O[4];
; #pragma unroll
;     for (int md = 0; md < 4; ++md)
; #pragma unroll
;         for (int i = 0; i < 16; ++i) O[md][i] = 0.f;
;     float m_run = -1e30f, l_run = 0.f;
;     if (TYPE == 2 && kh == 0) { m_run = p->sinks[layer * 8 + h] * LOG2E; l_run = (hh == 0) ? 1.f : 0.f; }
;     constexpr int GK = (DQ == 192) ? 3 : 4, NG = NKS / GK;
;     A_LSTORE(A, 0); __syncthreads();
;     if (kh == 0) __builtin_amdgcn_s_setprio(2);
; #pragma unroll 1
;     for (int j = j_lo; j <= j_hi; ++j) {
;         const int buf = (j - j_lo) & 1;
;         if (j < j_hi) A_GLOAD(A, j + 1);
.LBB0_402:
	s_or_b32 s13, s51, 1
	s_ashr_i32 s56, s16, 8
	s_cmp_gt_i32 s12, s13
	v_lshlrev_b32_e32 v155, 2, v3
	s_cbranch_scc1 .LBB0_413
	s_lshl_b32 s13, s56, 5
	v_or_b32_e32 v0, s13, v2
	s_add_i32 s16, s15, 0xf65
	v_mul_lo_u32 v163, v0, s84
	v_add_u32_e32 v0, s16, v2
	s_lshl_b32 s16, s12, 6
	s_add_i32 s59, s16, s13
	v_lshlrev_b32_e32 v16, 3, v3
	v_or_b32_e32 v3, s59, v155
	v_sub_u32_e32 v0, v0, v3
	s_lshl_b32 s14, s14, 7
	v_subrev_u32_e32 v165, s14, v0
	s_add_i32 s14, s14, s59
	s_addk_i32 s14, 0xf080
	v_or_b32_e32 v0, s14, v155
	v_sub_u32_e32 v0, v0, v2
	v_mov_b32_e32 v14, v1
	v_mov_b32_e32 v15, v1
	v_and_b32_e32 v244, 7, v2
	v_lshrrev_b32_e32 v245, 3, v2
	v_mad_u32_u24 v244, v244, 18, v245
	v_mul_u32_u24_e32 v164, 0x88, v244
	v_subrev_u32_e32 v166, s15, v0
	v_mov_b32_e32 v0, v1
	v_mov_b32_e32 v2, v1
	v_mov_b32_e32 v3, v1
	v_mov_b32_e32 v4, v1
	v_mov_b32_e32 v5, v1
	v_mov_b32_e32 v6, v1
	v_mov_b32_e32 v7, v1
	v_mov_b32_e32 v8, v1
	v_mov_b32_e32 v9, v1
	v_mov_b32_e32 v10, v1
	v_mov_b32_e32 v11, v1
	v_mov_b32_e32 v12, v1
	v_mov_b32_e32 v13, v1
	v_lshlrev_b32_e32 v167, 1, v16
	v_mov_b64_e32 v[46:47], v[14:15]
	v_mov_b64_e32 v[30:31], v[14:15]
	v_mov_b64_e32 v[78:79], v[14:15]
	v_mov_b64_e32 v[62:63], v[14:15]
	v_mul_u32_u24_e32 v162, 17, v157
	s_or_b32 s57, s58, 31
	s_addk_i32 s58, 0xff80
	v_mov_b64_e32 v[44:45], v[12:13]
	v_mov_b64_e32 v[42:43], v[10:11]
	v_mov_b64_e32 v[40:41], v[8:9]
	v_mov_b64_e32 v[38:39], v[6:7]
	v_mov_b64_e32 v[36:37], v[4:5]
	v_mov_b64_e32 v[34:35], v[2:3]
	v_mov_b64_e32 v[32:33], v[0:1]
	v_mov_b64_e32 v[28:29], v[12:13]
	v_mov_b64_e32 v[26:27], v[10:11]
	v_mov_b64_e32 v[24:25], v[8:9]
	v_mov_b64_e32 v[22:23], v[6:7]
	v_mov_b64_e32 v[20:21], v[4:5]
	v_mov_b64_e32 v[18:19], v[2:3]
	v_mov_b64_e32 v[16:17], v[0:1]
	v_mov_b64_e32 v[76:77], v[12:13]
	v_mov_b64_e32 v[74:75], v[10:11]
	v_mov_b64_e32 v[72:73], v[8:9]
	v_mov_b64_e32 v[70:71], v[6:7]
	v_mov_b64_e32 v[68:69], v[4:5]
	v_mov_b64_e32 v[66:67], v[2:3]
	v_mov_b64_e32 v[64:65], v[0:1]
	v_mov_b64_e32 v[60:61], v[12:13]
	v_mov_b64_e32 v[58:59], v[10:11]
	v_mov_b64_e32 v[56:57], v[8:9]
	v_mov_b64_e32 v[54:55], v[6:7]
	v_mov_b64_e32 v[52:53], v[4:5]
	v_mov_b64_e32 v[50:51], v[2:3]
	v_mov_b64_e32 v[48:49], v[0:1]
	s_add_i32 s60, s12, 1
	s_ashr_i32 s61, s60, 31
	s_lshl_b64 s[60:61], s[60:61], 6
	v_mov_b32_e32 v248, 0x5040100
	v_mov_b32_e32 v249, 0x7060302
	s_mov_b32 s98, 0x8000
	s_mov_b32 s99, 0
	v_lshl_add_u64 v[232:233], s[60:61], 0, v[146:147]
	v_lshl_add_u64 v[234:235], s[60:61], 0, v[148:149]
	v_lshl_add_u64 v[236:237], s[60:61], 0, v[150:151]
	v_lshlrev_b64 v[232:233], 9, v[232:233]
	v_lshlrev_b64 v[234:235], 9, v[234:235]
	v_lshlrev_b64 v[236:237], 9, v[236:237]
	v_lshl_add_u64 v[232:233], v[144:145], 0, v[232:233]
	v_lshl_add_u64 v[234:235], v[144:145], 0, v[234:235]
	v_lshl_add_u64 v[236:237], v[152:153], 0, v[236:237]
	s_waitcnt vmcnt(0)
	s_branch .LBB0_406
.LBB0_404:
	s_xor_b32 s16, s60, 1
	s_mul_i32 s16, s16, 0x8f70
	s_add_i32 s16, s16, 16
	v_lshl_add_u32 v0, v157, 1, s16
	v_add_u32_e32 v2, v0, v159
	v_add_u32_e32 v0, v0, v160
	s_waitcnt vmcnt(3)
	ds_write_b128 v2, v[96:99]
	s_waitcnt vmcnt(2)
	ds_write_b128 v0, v[100:103]
	s_waitcnt vmcnt(1)
	v_add3_u32 v2, s16, v162, v161
	s_waitcnt vmcnt(0)
	v_perm_b32 v0, v128, v116, v248
	v_perm_b32 v3, v128, v116, v249
	v_add_u32_e32 v2, 0x4400, v2
	ds_write_b32 v2, v0
	ds_write_b32 v2, v3 offset:2448
	v_perm_b32 v0, v129, v117, v248
	v_perm_b32 v3, v129, v117, v249
	ds_write_b32 v2, v0 offset:4896
	ds_write_b32 v2, v3 offset:7344
	v_perm_b32 v0, v130, v118, v248
	v_perm_b32 v3, v130, v118, v249
	ds_write_b32 v2, v0 offset:9792
	ds_write_b32 v2, v3 offset:12240
	v_perm_b32 v0, v131, v119, v248
	v_perm_b32 v3, v131, v119, v249
	ds_write_b32 v2, v0 offset:14688
	ds_write_b32 v2, v3 offset:17136

; template <int DQ, int TYPE>
; __device__ __forceinline__ void attn_item(PP p, int layer, int b, int h, int qt, char* lds, const int tid_, unsigned* next_ctr, volatile XLAS unsigned* slot) {
;     ...
;     f32x16 O[4];
; #pragma unroll
;     for (int md = 0; md < 4; ++md)
; #pragma unroll
;         for (int i = 0; i < 16; ++i) O[md][i] = 0.f;
;     float m_run = -1e30f, l_run = 0.f;
;     if (TYPE == 2 && kh == 0) { m_run = p->sinks[layer * 8 + h] * LOG2E; l_run = (hh == 0) ? 1.f : 0.f; }
;     constexpr int GK = (DQ == 192) ? 3 : 4, NG = NKS / GK;
;     A_LSTORE(A, 0); __syncthreads();
;     if (kh == 0) __builtin_amdgcn_s_setprio(2);
; #pragma unroll 1
;     for (int j = j_lo; j <= j_hi; ++j) {
.LBB0_637:
	s_waitcnt vmcnt(0)
	s_ashr_i32 s54, s88, 8
	s_lshl_b32 s58, s54, 5
	v_or_b32_e32 v2, s58, v154
	v_mov_b32_e32 v18, v1
	v_mov_b32_e32 v19, v1
	v_mov_b32_e32 v32, v1
	v_mov_b32_e32 v33, v1
	v_mul_lo_u32 v162, v2, s84
	s_lshl_b32 s12, s49, 1
	v_mov_b32_e32 v20, v1
	v_mov_b32_e32 v21, v1
	v_mov_b32_e32 v22, v1
	v_mov_b32_e32 v23, v1
	v_mov_b32_e32 v24, v1
	v_mov_b32_e32 v25, v1
	v_mov_b32_e32 v26, v1
	v_mov_b32_e32 v27, v1
	v_mov_b32_e32 v28, v1
	v_mov_b32_e32 v29, v1
	v_mov_b32_e32 v30, v1
	v_mov_b32_e32 v31, v1
	v_mov_b64_e32 v[2:3], v[18:19]
	v_mov_b64_e32 v[64:65], v[32:33]
	v_mov_b64_e32 v[48:49], v[32:33]
	v_mul_u32_u24_e32 v161, 17, v185
	s_lshl_b32 s57, s80, 1
	s_or_b32 s59, s95, 31
	v_and_b32_e32 v244, 7, v154
	v_lshrrev_b32_e32 v245, 3, v154
	v_mad_u32_u24 v244, v244, 18, v245
	v_mul_u32_u24_e32 v163, 0x88, v244
	v_lshlrev_b32_e32 v147, 2, v155
	s_sub_i32 s60, 64, s12
	s_mov_b32 s61, 0
	v_mov_b32_e32 v164, 0
	v_mov_b32_e32 v176, 0xf149f2ca
	s_mov_b32 s62, s58
	v_mov_b64_e32 v[4:5], v[20:21]
	v_mov_b64_e32 v[6:7], v[22:23]
	v_mov_b64_e32 v[8:9], v[24:25]
	v_mov_b64_e32 v[10:11], v[26:27]
	v_mov_b64_e32 v[12:13], v[28:29]
	v_mov_b64_e32 v[14:15], v[30:31]
	v_mov_b64_e32 v[16:17], v[32:33]
	v_mov_b64_e32 v[62:63], v[30:31]
	v_mov_b64_e32 v[60:61], v[28:29]
	v_mov_b64_e32 v[58:59], v[26:27]
	v_mov_b64_e32 v[56:57], v[24:25]
	v_mov_b64_e32 v[54:55], v[22:23]
	v_mov_b64_e32 v[52:53], v[20:21]
	v_mov_b64_e32 v[50:51], v[18:19]
	v_mov_b64_e32 v[46:47], v[30:31]
	v_mov_b64_e32 v[44:45], v[28:29]
	v_mov_b64_e32 v[42:43], v[26:27]
	v_mov_b64_e32 v[40:41], v[24:25]
	v_mov_b64_e32 v[38:39], v[22:23]
	v_mov_b64_e32 v[36:37], v[20:21]
	v_mov_b64_e32 v[34:35], v[18:19]
	v_mov_b32_e32 v248, 0x5040100
	v_mov_b32_e32 v249, 0x7060302
	s_mov_b32 s98, 0x10000
	s_mov_b32 s99, 0
	v_lshlrev_b64 v[232:233], 10, v[166:167]
	v_lshlrev_b64 v[234:235], 10, v[168:169]
	v_lshlrev_b64 v[236:237], 10, v[170:171]
	v_lshl_add_u64 v[232:233], v[148:149], 0, v[232:233]
	v_lshl_add_u64 v[234:235], v[148:149], 0, v[234:235]
	v_lshl_add_u64 v[236:237], v[150:151], 0, v[236:237]
	v_lshl_add_u64 v[232:233], s[98:99], 0, v[232:233]
	v_lshl_add_u64 v[234:235], s[98:99], 0, v[234:235]
	v_lshl_add_u64 v[236:237], s[98:99], 0, v[236:237]
	s_cmp_le_u32 s61, s57
	s_cselect_b64 s[12:13], -1, 0
	s_cmp_gt_u32 s61, s57
	s_cbranch_scc1 .LBB0_640
	s_branch .LBB0_639

.LBB0_647:
	s_xor_b32 s12, s63, 1
	s_mul_i32 s12, s12, 0x8f70
	s_add_i32 s12, s12, 16
	v_lshl_add_u32 v66, v185, 1, s12
	v_add_u32_e32 v67, v66, v158
	v_add_u32_e32 v66, v66, v159
	s_waitcnt vmcnt(3)
	ds_write_b128 v67, v[82:85]
	s_waitcnt vmcnt(2)
	ds_write_b128 v66, v[86:89]
	s_waitcnt vmcnt(1)
	v_add3_u32 v67, s12, v161, v160
	s_waitcnt vmcnt(0)
	v_perm_b32 v66, v118, v106, v248
	v_perm_b32 v68, v118, v106, v249
	v_add_u32_e32 v67, 0x4400, v67
	ds_write_b32 v67, v66
	ds_write_b32 v67, v68 offset:2448
	v_perm_b32 v66, v119, v107, v248
	v_perm_b32 v68, v119, v107, v249
	ds_write_b32 v67, v66 offset:4896
	ds_write_b32 v67, v68 offset:7344
	v_perm_b32 v66, v120, v108, v248
	v_perm_b32 v68, v120, v108, v249
	ds_write_b32 v67, v66 offset:9792
	ds_write_b32 v67, v68 offset:12240
	v_perm_b32 v66, v121, v109, v248
	v_perm_b32 v68, v121, v109, v249
	ds_write_b32 v67, v66 offset:14688
	ds_write_b32 v67, v68 offset:17136

; __device__ __forceinline__ bf16_t cvt_bf16(float v) { return (bf16_t)(cvt_pk_bf16(v, 0.f) & 0xffffu); }
; template <int DQ, int TYPE>
; __device__ __forceinline__ void attn_item(PP p, int layer, int b, int h, int qt, char* lds, const int tid_, unsigned* next_ctr, volatile XLAS unsigned* slot) {
;     ...
;             for (int kk = 0; kk < 2; ++kk) {
;                 bf16x8 x1 = qf[8 + kk], x2 = qf[10 + kk], o1, o2;
; #pragma unroll
;                 for (int j = 0; j < 8; ++j) {
;                     const int f = 16 * kk + 8 * hh + j;
;                     const float cs = r64[2 * f], sn = r64[2 * f + 1];
;                     const float a = __uint_as_float(((unsigned)(unsigned short)x1[j]) << 16), bb = __uint_as_float(((unsigned)(unsigned short)x2[j]) << 16);
;                     o1[j] = (short)cvt_bf16(a * cs - bb * sn); o2[j] = (short)cvt_bf16(bb * cs + a * sn);
;                 }
;                 qf[8 + kk] = o1; qf[10 + kk] = o2;
;             }
;     ...
;     f32x16 O[4];
; #pragma unroll
;     for (int md = 0; md < 4; ++md)
; #pragma unroll
;         for (int i = 0; i < 16; ++i) O[md][i] = 0.f;
;     float m_run = -1e30f, l_run = 0.f;
;     if (TYPE == 2 && kh == 0) { m_run = p->sinks[layer * 8 + h] * LOG2E; l_run = (hh == 0) ? 1.f : 0.f; }
;     constexpr int GK = (DQ == 192) ? 3 : 4, NG = NKS / GK;
;     A_LSTORE(A, 0); __syncthreads();
;     if (kh == 0) __builtin_amdgcn_s_setprio(2);
; #pragma unroll 1
;     for (int j = j_lo; j <= j_hi; ++j) {
.LBB0_661:
	s_ashr_i32 s56, s14, 8
	v_lshl_add_u64 v[190:191], s[12:13], 0, v[0:1]
	s_lshl_b32 s17, s56, 5
	s_mov_b32 s12, 0x5040100
	v_or_b32_e32 v18, s17, v154
	v_perm_b32 v140, v35, v34, s12
	v_mov_b32_e32 v34, v1
	v_mov_b32_e32 v35, v1
	v_mov_b32_e32 v48, v1
	v_mov_b32_e32 v49, v1
	v_mul_lo_u32 v196, v18, s51
	v_perm_b32 v137, v30, v28, s12
	v_perm_b32 v136, v27, v26, s12
	v_perm_b32 v135, v25, v24, s12
	v_perm_b32 v134, v23, v22, s12
	v_perm_b32 v141, v9, v36, s12
	v_perm_b32 v139, v33, v32, s12
	v_perm_b32 v138, v31, v29, s12
	v_perm_b32 v145, v17, v16, s12
	v_perm_b32 v144, v12, v15, s12
	v_perm_b32 v143, v11, v14, s12
	v_perm_b32 v142, v10, v19, s12
	v_perm_b32 v149, v5, v8, s12
	v_perm_b32 v148, v4, v7, s12
	v_perm_b32 v147, v3, v6, s12
	v_perm_b32 v146, v2, v13, s12
	s_lshl_b32 s12, s49, 1
	v_mov_b32_e32 v36, v1
	v_mov_b32_e32 v37, v1
	v_mov_b32_e32 v38, v1
	v_mov_b32_e32 v39, v1
	v_mov_b32_e32 v40, v1
	v_mov_b32_e32 v41, v1
	v_mov_b32_e32 v42, v1
	v_mov_b32_e32 v43, v1
	v_mov_b32_e32 v44, v1
	v_mov_b32_e32 v45, v1
	v_mov_b32_e32 v46, v1
	v_mov_b32_e32 v47, v1
	v_mov_b64_e32 v[64:65], v[48:49]
	v_mov_b64_e32 v[2:3], v[34:35]
	v_mov_b64_e32 v[18:19], v[34:35]
	v_mul_u32_u24_e32 v195, 17, v185
	s_lshl_b32 s16, s80, 1
	s_or_b32 s50, s15, 31
	v_and_b32_e32 v244, 7, v154
	v_lshrrev_b32_e32 v245, 3, v154
	v_mad_u32_u24 v244, v244, 18, v245
	v_mul_u32_u24_e32 v197, 0x88, v244
	v_lshlrev_b32_e32 v187, 2, v155
	s_sub_i32 s49, 64, s12
	s_mov_b32 s51, 0
	v_mov_b32_e32 v199, 0
	v_mov_b32_e32 v205, 0xf149f2ca
	v_lshlrev_b32_e32 v198, 1, v153
	s_mov_b32 s57, s17
	v_mov_b64_e32 v[62:63], v[46:47]
	v_mov_b64_e32 v[60:61], v[44:45]
	v_mov_b64_e32 v[58:59], v[42:43]
	v_mov_b64_e32 v[56:57], v[40:41]
	v_mov_b64_e32 v[54:55], v[38:39]
	v_mov_b64_e32 v[52:53], v[36:37]
	v_mov_b64_e32 v[50:51], v[34:35]
	v_mov_b64_e32 v[4:5], v[36:37]
	v_mov_b64_e32 v[6:7], v[38:39]
	v_mov_b64_e32 v[8:9], v[40:41]
	v_mov_b64_e32 v[10:11], v[42:43]
	v_mov_b64_e32 v[12:13], v[44:45]
	v_mov_b64_e32 v[14:15], v[46:47]
	v_mov_b64_e32 v[16:17], v[48:49]
	v_mov_b64_e32 v[20:21], v[36:37]
	v_mov_b64_e32 v[22:23], v[38:39]
	v_mov_b64_e32 v[24:25], v[40:41]
	v_mov_b64_e32 v[26:27], v[42:43]
	v_mov_b64_e32 v[28:29], v[44:45]
	v_mov_b64_e32 v[30:31], v[46:47]
	v_mov_b64_e32 v[32:33], v[48:49]
	v_mov_b32_e32 v248, 0x5040100
	v_mov_b32_e32 v249, 0x7060302
	s_mov_b32 s98, 0x20000
	s_mov_b32 s99, 0
	v_lshlrev_b64 v[232:233], 11, v[166:167]
	v_lshlrev_b64 v[234:235], 11, v[168:169]
	v_lshlrev_b64 v[236:237], 11, v[170:171]
	v_lshlrev_b64 v[238:239], 7, v[174:175]
	v_lshl_add_u64 v[232:233], v[176:177], 0, v[232:233]
	v_lshl_add_u64 v[234:235], v[176:177], 0, v[234:235]
	v_lshl_add_u64 v[236:237], v[176:177], 0, v[236:237]
	v_lshl_add_u64 v[238:239], v[190:191], 0, v[238:239]
	v_lshl_add_u64 v[232:233], s[98:99], 0, v[232:233]
	v_lshl_add_u64 v[234:235], s[98:99], 0, v[234:235]
	v_lshl_add_u64 v[236:237], s[98:99], 0, v[236:237]
	v_add_co_u32_e32 v238, vcc, 0x2000, v238
	v_addc_co_u32_e32 v239, vcc, 0, v239, vcc
	s_cmp_le_u32 s51, s16
	s_cselect_b64 s[12:13], -1, 0
	s_cmp_gt_u32 s51, s16
	s_cbranch_scc1 .LBB0_664
	s_branch .LBB0_663

.LBB0_671:
	s_xor_b32 s12, s58, 1
	s_mul_i32 s12, s12, 0xaf70
	s_add_i32 s12, s12, 16
	v_lshl_add_u32 v66, v185, 1, s12
	v_add_u32_e32 v67, v66, v189
	v_add_u32_e32 v66, v66, v193
	s_waitcnt vmcnt(4)
	ds_write_b128 v67, v[86:89]
	s_waitcnt vmcnt(3)
	ds_write_b128 v66, v[90:93]
	v_add3_u32 v66, s12, v194, v0
	v_lshlrev_b32_e32 v67, 1, v170
	s_waitcnt vmcnt(2)
	ds_write_b128 v66, v[118:121] offset:256
	s_waitcnt vmcnt(1)
	v_add3_u32 v67, s12, v195, v67
	s_waitcnt vmcnt(0)
	v_perm_b32 v66, v122, v114, v248
	v_perm_b32 v68, v122, v114, v249
	v_add_u32_e32 v67, 0x6400, v67
	ds_write_b32 v67, v66
	ds_write_b32 v67, v68 offset:2448
	v_perm_b32 v66, v123, v115, v248
	v_perm_b32 v68, v123, v115, v249
	ds_write_b32 v67, v66 offset:4896
	ds_write_b32 v67, v68 offset:7344
	v_perm_b32 v66, v124, v116, v248
	v_perm_b32 v68, v124, v116, v249
	ds_write_b32 v67, v66 offset:9792
	ds_write_b32 v67, v68 offset:12240
	v_perm_b32 v66, v125, v117, v248
	v_perm_b32 v68, v125, v117, v249
	ds_write_b32 v67, v66 offset:14688
	ds_write_b32 v67, v68 offset:17136
